# idxsel scoring loop hand-scheduled: two MFMA accumulators so the next query pair's MFMA chain runs under the relu/weight VALU chain; redundant canonicalising v_max folded into the relu
# baseline (speedup 1.0000x reference)
; DI void idxsel_phase(unsigned char* lds, const bf16_t* __restrict__ hbuf, const bf16_t* __restrict__ ikn, const float* __restrict__ iwf, u64* __restrict__ bits, unsigned* ctr) {
;     ...
;           for (int u = 0; u < 4; ++u) {
;             f32x16 acc = {};
; #pragma unroll
;             for (int ks = 0; ks < 4; ++ks) acc = __builtin_amdgcn_mfma_f32_32x32x16_bf16(a[u][ks], bfr[ks], acc, 0, 0, 0);
;             float sc = 0.f;
; #pragma unroll
;             for (int r4 = 0; r4 < 4; ++r4)
; #pragma unroll
;               for (int jj = 0; jj < 4; ++jj) sc += fmaxf(acc[4 * r4 + jj], 0.f) * w[u][r4][jj];
;             sc_l[(2 * u + kh) * 4096 + 32 * kt + i32] = sc;
;           }
.LBB0_945:
	s_or_b64 exec, exec, s[6:7]
	s_and_b64 s[0:1], exec, s[0:1]
	s_or_b64 s[4:5], s[0:1], s[4:5]
	v_mfma_f32_32x32x16_bf16 v[2:17], v[18:21], v[174:177], 0
	v_mfma_f32_32x32x16_bf16 v[2:17], v[22:25], v[170:173], v[2:17]
	v_mfma_f32_32x32x16_bf16 v[2:17], v[26:29], v[166:169], v[2:17]
	v_mfma_f32_32x32x16_bf16 v[2:17], v[30:33], v[146:149], v[2:17]
	v_mfma_f32_32x32x16_bf16 v[194:209], v[34:37], v[174:177], 0
	v_mfma_f32_32x32x16_bf16 v[194:209], v[38:41], v[170:173], v[194:209]
	v_mfma_f32_32x32x16_bf16 v[194:209], v[42:45], v[166:169], v[194:209]
	v_mfma_f32_32x32x16_bf16 v[194:209], v[46:49], v[146:149], v[194:209]
	v_add_u32_e32 v211, 0xffff0000, v0
	s_nop 8
	v_max_f32_e32 v214, 0, v2
	v_fma_f32 v213, v130, v214, 0
	v_max_f32_e32 v214, 0, v3
	v_fmac_f32_e32 v213, v131, v214
	v_max_f32_e32 v214, 0, v4
	v_fmac_f32_e32 v213, v132, v214
	v_max_f32_e32 v214, 0, v5
	v_fmac_f32_e32 v213, v133, v214
	v_max_f32_e32 v214, 0, v6
	v_fmac_f32_e32 v213, v134, v214
	v_max_f32_e32 v214, 0, v7
	v_fmac_f32_e32 v213, v135, v214
	v_max_f32_e32 v214, 0, v8
	v_fmac_f32_e32 v213, v136, v214
	v_max_f32_e32 v214, 0, v9
	v_fmac_f32_e32 v213, v137, v214
	v_max_f32_e32 v214, 0, v10
	v_fmac_f32_e32 v213, v138, v214
	v_max_f32_e32 v214, 0, v11
	v_fmac_f32_e32 v213, v139, v214
	v_max_f32_e32 v214, 0, v12
	v_fmac_f32_e32 v213, v140, v214
	v_max_f32_e32 v214, 0, v13
	v_fmac_f32_e32 v213, v141, v214
	v_max_f32_e32 v214, 0, v14
	v_fmac_f32_e32 v213, v142, v214
	v_max_f32_e32 v214, 0, v15
	v_fmac_f32_e32 v213, v143, v214
	v_max_f32_e32 v214, 0, v16
	v_fmac_f32_e32 v213, v144, v214
	v_max_f32_e32 v214, 0, v17
	v_fmac_f32_e32 v213, v145, v214
	ds_write_b32 v211, v213
	v_mfma_f32_32x32x16_bf16 v[2:17], v[50:53], v[174:177], 0
	v_mfma_f32_32x32x16_bf16 v[2:17], v[54:57], v[170:173], v[2:17]
	v_mfma_f32_32x32x16_bf16 v[2:17], v[58:61], v[166:169], v[2:17]
	v_mfma_f32_32x32x16_bf16 v[2:17], v[62:65], v[146:149], v[2:17]
	v_add_u32_e32 v211, 0xffff8000, v0
	v_max_f32_e32 v214, 0, v194
	v_fma_f32 v215, v114, v214, 0
	v_max_f32_e32 v214, 0, v195
	v_fmac_f32_e32 v215, v115, v214
	v_max_f32_e32 v214, 0, v196
	v_fmac_f32_e32 v215, v116, v214
	v_max_f32_e32 v214, 0, v197
	v_fmac_f32_e32 v215, v117, v214
	v_max_f32_e32 v214, 0, v198
	v_fmac_f32_e32 v215, v118, v214
	v_max_f32_e32 v214, 0, v199
	v_fmac_f32_e32 v215, v119, v214
	v_max_f32_e32 v214, 0, v200
	v_fmac_f32_e32 v215, v120, v214
	v_max_f32_e32 v214, 0, v201
	v_fmac_f32_e32 v215, v121, v214
	v_max_f32_e32 v214, 0, v202
	v_fmac_f32_e32 v215, v122, v214
	v_max_f32_e32 v214, 0, v203
	v_fmac_f32_e32 v215, v123, v214
	v_max_f32_e32 v214, 0, v204
	v_fmac_f32_e32 v215, v124, v214
	v_max_f32_e32 v214, 0, v205
	v_fmac_f32_e32 v215, v125, v214
	v_max_f32_e32 v214, 0, v206
	v_fmac_f32_e32 v215, v126, v214
	v_max_f32_e32 v214, 0, v207
	v_fmac_f32_e32 v215, v127, v214
	v_max_f32_e32 v214, 0, v208
	v_fmac_f32_e32 v215, v128, v214
	v_max_f32_e32 v214, 0, v209
	v_fmac_f32_e32 v215, v129, v214
	ds_write_b32 v211, v215
	v_mfma_f32_32x32x16_bf16 v[194:209], v[66:69], v[174:177], 0
	v_mfma_f32_32x32x16_bf16 v[194:209], v[70:73], v[170:173], v[194:209]
	v_mfma_f32_32x32x16_bf16 v[194:209], v[74:77], v[166:169], v[194:209]
	v_mfma_f32_32x32x16_bf16 v[194:209], v[78:81], v[146:149], v[194:209]
	v_max_f32_e32 v214, 0, v2
	v_fma_f32 v210, v98, v214, 0
	v_max_f32_e32 v214, 0, v3
	v_fmac_f32_e32 v210, v99, v214
	v_max_f32_e32 v214, 0, v4
	v_fmac_f32_e32 v210, v100, v214
	v_max_f32_e32 v214, 0, v5
	v_fmac_f32_e32 v210, v101, v214
	v_max_f32_e32 v214, 0, v6
	v_fmac_f32_e32 v210, v102, v214
	v_max_f32_e32 v214, 0, v7
	v_fmac_f32_e32 v210, v103, v214
	v_max_f32_e32 v214, 0, v8
	v_fmac_f32_e32 v210, v104, v214
	v_max_f32_e32 v214, 0, v9
	v_fmac_f32_e32 v210, v105, v214
	v_max_f32_e32 v214, 0, v10
	v_fmac_f32_e32 v210, v106, v214
	v_max_f32_e32 v214, 0, v11
	v_fmac_f32_e32 v210, v107, v214
	v_max_f32_e32 v214, 0, v12
	v_fmac_f32_e32 v210, v108, v214
	v_max_f32_e32 v214, 0, v13
	v_fmac_f32_e32 v210, v109, v214
	v_max_f32_e32 v214, 0, v14
	v_fmac_f32_e32 v210, v110, v214
	v_max_f32_e32 v214, 0, v15
	v_fmac_f32_e32 v210, v111, v214
	v_max_f32_e32 v214, 0, v16
	v_fmac_f32_e32 v210, v112, v214
	v_max_f32_e32 v214, 0, v17
	v_fmac_f32_e32 v210, v113, v214
	s_waitcnt vmcnt(3)
	v_mov_b32_e32 v174, v150
	v_mov_b32_e32 v175, v151
	v_mov_b32_e32 v176, v152
	v_mov_b32_e32 v177, v153
	s_waitcnt vmcnt(2)
	v_mov_b32_e32 v170, v154
	v_mov_b32_e32 v171, v155
	v_mov_b32_e32 v172, v156
	v_mov_b32_e32 v173, v157
	s_waitcnt vmcnt(1)
	v_mov_b32_e32 v166, v158
	v_mov_b32_e32 v167, v159
	v_mov_b32_e32 v168, v160
	v_mov_b32_e32 v169, v161
	s_waitcnt vmcnt(0)
	v_mov_b32_e32 v146, v162
	v_mov_b32_e32 v147, v163
	v_mov_b32_e32 v148, v164
	v_mov_b32_e32 v149, v165
	v_max_f32_e32 v214, 0, v194
	v_fma_f32 v216, v82, v214, 0
	v_max_f32_e32 v214, 0, v195
	v_fmac_f32_e32 v216, v83, v214
	v_max_f32_e32 v214, 0, v196
	v_fmac_f32_e32 v216, v84, v214
	v_max_f32_e32 v214, 0, v197
	v_fmac_f32_e32 v216, v85, v214
	v_max_f32_e32 v214, 0, v198
	v_fmac_f32_e32 v216, v86, v214
	v_max_f32_e32 v214, 0, v199
	v_fmac_f32_e32 v216, v87, v214
	v_max_f32_e32 v214, 0, v200
	v_fmac_f32_e32 v216, v88, v214
	v_max_f32_e32 v214, 0, v201
	v_fmac_f32_e32 v216, v89, v214
	v_max_f32_e32 v214, 0, v202
	v_fmac_f32_e32 v216, v90, v214
	v_max_f32_e32 v214, 0, v203
	v_fmac_f32_e32 v216, v91, v214
	v_max_f32_e32 v214, 0, v204
	v_fmac_f32_e32 v216, v92, v214
	v_max_f32_e32 v214, 0, v205
	v_fmac_f32_e32 v216, v93, v214
	v_max_f32_e32 v214, 0, v206
	v_fmac_f32_e32 v216, v94, v214
	v_max_f32_e32 v214, 0, v207
	v_fmac_f32_e32 v216, v95, v214
	v_max_f32_e32 v214, 0, v208
	v_fmac_f32_e32 v216, v96, v214
	v_max_f32_e32 v214, 0, v209
	v_fmac_f32_e32 v216, v97, v214
	ds_write2st64_b32 v0, v210, v216 offset1:128
	v_add_u32_e32 v0, 0x400, v0
	s_andn2_b64 exec, exec, s[4:5]
	s_cbranch_execz .LBB0_948
